# v15 + P13->P14 seam workgroup-local (each P14 unit reads only its own workgroup's P13 output): grid barrier replaced by workgroup sync + L1 invalidate
# speedup vs baseline: 1.0036x; 1.0036x over previous
.LBB0_1314:
	s_waitcnt vmcnt(0)
	s_load_dwordx2 s[2:3], s[0:1], 0x310
	s_waitcnt lgkmcnt(0)
	s_cmp_gt_i32 s3, 14
	s_cselect_b64 s[6:7], -1, 0
	s_and_b64 s[2:3], s[4:5], s[6:7]
	s_andn2_b64 vcc, exec, s[2:3]
	s_cbranch_vccnz .LBB0_1368
	s_cmpk_lg_i32 s80, 0x100
	s_cbranch_scc1 .Lwg_orig_0
	s_waitcnt vmcnt(0)
	s_barrier
	s_and_saveexec_b64 s[4:5], s[86:87]
	s_cbranch_execz .Lwg_done_0
	buffer_inv sc1
	s_waitcnt vmcnt(0)
